# v33 + attention pass prologue: |q|^2 consumer moved after the K/V tile 0/1 loads are issued (Q-row load latency overlaps tile load latency)
# baseline (speedup 1.0000x reference)
; template <bool GRPB> __device__ __forceinline__ void attn_pass(const float mbK, const float bmax2, const int pass, float* __restrict__ scr, bf16* __restrict__ mixrow, const float lam, const float* __restrict__ gsub, const float one_m_li, ...
;     ...
;   const float cL = __uint_as_float(__builtin_amdgcn_readfirstlane(__float_as_uint(tb2[0]))), cR = __uint_as_float(__builtin_amdgcn_readfirstlane(__float_as_uint(tb2[384])));
;   const int qw = __builtin_amdgcn_readfirstlane(q0seq + wid * 32), qpos = qw + r32;
;   float m_reg, l_reg = 0; bf16x8 qr[4]; f32x16 o[4];
; #pragma unroll
;   for (int d = 0; d < 4; ++d) o[d] = f32x16{};
;   const bf16* Qw = Qb + (long)(wid * 32 + r32) * LDK + hi * 8;
; #pragma unroll
;   for (int d0 = 0; d0 < 4; ++d0) qr[d0] = *(const GAS bf16x8*)(Qw + d0 * 16);
;   { float qs = 0.f;
; #pragma unroll
;     for (int d0 = 0; d0 < 4; ++d0)
; #pragma unroll
;       for (int j = 0; j < 8; ++j) { const float v = bf2f((unsigned short)qr[d0][j]); qs = fmaf(v, v, qs); }
;     { auto rr = __builtin_amdgcn_permlane32_swap(__float_as_uint(qs), __float_as_uint(qs), false, false); qs = __uint_as_float(rr[0]) + __uint_as_float(rr[1]); }
;     m_reg = __builtin_sqrtf(qs) * mbK + bmax2 + 0.25f; }
;   const int sr = tid >> 4, sc = (tid & 15) * 8, vst0 = v_st(sr, sc), vst1 = v_st(32 + sr, sc);
;   const int kr = tid >> 3, kc = (tid & 7) * 8, kst = KSWZ64(kr, kc * 2);
;   const int vb0 = (int)(uintptr_t)V_lds + v_rd_base(lane);
;   struct { bf16x8 vs0, vs1, ks0; } sr_[2];
;     ...
;   f32x16 pA0, pA1, pB0, pB1; float mnA, mnB, alA, alB; bf16x8 pa0, pa1, pa2, pa3; constexpr int NT = SEQ / KVBLK;
;   __syncthreads();
;   SLOAD(0, 0); SLOAD(1, KVBLK); asm volatile("s_waitcnt vmcnt(0)" ::: "memory"); SWRITE(0, 0); SWRITE(1, 1);
; __device__ __forceinline__ void attn_phase(const Params& p, int e, char* lds) {
;     ...
;     const unsigned* kmx = (const unsigned*)(p.ws + WS_KMX) + e * 128 + b * 8 + h * 2;
;     const float mbK0 = __uint_as_float(__builtin_amdgcn_readfirstlane(__float_as_uint(C1 * 1.01f * __builtin_sqrtf(2.0f * __uint_as_float(kmx[0])))));
;     const float mbK1 = __uint_as_float(__builtin_amdgcn_readfirstlane(__float_as_uint(C1 * 1.01f * __builtin_sqrtf(2.0f * __uint_as_float(kmx[1])))));
;     bmax2 = __uint_as_float(__builtin_amdgcn_readfirstlane(__float_as_uint(bmax2)));
;     if (__builtin_amdgcn_readfirstlane(wid) & 1) {
.LBB0_295:
	s_lshl_b32 s0, s59, 8
	s_ashr_i32 s48, s59, 6
	s_and_b32 s39, s0, 0xf00
	s_ashr_i32 s49, s48, 31
	s_lshl_b32 s0, s48, 3
	s_lshl_b64 s[46:47], s[48:49], 12
	s_ashr_i32 s1, s0, 31
	s_or_b32 s46, s46, s39
	s_lshl_b64 s[0:1], s[0:1], 2
	s_add_u32 s0, s35, s0
	s_addc_u32 s1, s56, s1
	s_lshl_b32 s2, s44, 3
	s_add_u32 s0, s0, s2
	s_addc_u32 s1, s1, 0
	v_mov_b64_e32 v[2:3], s[0:1]
	flat_load_dwordx2 v[2:3], v[2:3]
	s_mov_b32 s2, 0xf800000
	v_mov_b32_e32 v6, 0x3fba82f9
	v_readfirstlane_b32 s45, v0
	v_lshrrev_b32_e32 v0, 6, v232
	s_mov_b32 s10, 0xf800000
	v_mov_b32_e32 v198, 0x260
	s_waitcnt vmcnt(0) lgkmcnt(0)
	v_add_f32_e32 v1, v2, v2
	v_cmp_gt_f32_e32 vcc, s2, v1
	v_mul_f32_e32 v2, 0x4f800000, v1
	s_nop 0
	v_cndmask_b32_e32 v1, v1, v2, vcc
	v_sqrt_f32_e32 v2, v1
	s_nop 0
	v_add_u32_e32 v4, -1, v2
	v_fma_f32 v5, -v4, v2, v1
	v_cmp_ge_f32_e64 s[0:1], 0, v5
	v_add_u32_e32 v5, 1, v2
	s_nop 0
	v_cndmask_b32_e64 v4, v2, v4, s[0:1]
	v_fma_f32 v2, -v5, v2, v1
	v_cmp_lt_f32_e64 s[0:1], 0, v2
	s_nop 1
	v_cndmask_b32_e64 v2, v4, v5, s[0:1]
	v_mul_f32_e32 v4, 0x37800000, v2
	v_mov_b32_e32 v5, 0x260
	v_cndmask_b32_e32 v2, v2, v4, vcc
	v_cmp_class_f32_e32 vcc, v1, v5
	s_nop 1
	v_cndmask_b32_e32 v1, v2, v1, vcc
	s_nop 0
	v_readfirstlane_b32 s0, v1
	v_add_f32_e32 v1, v3, v3
	v_cmp_gt_f32_e32 vcc, s2, v1
	v_mul_f32_e32 v2, 0x4f800000, v1
	v_mul_f32_e32 v216, s0, v6
	v_cndmask_b32_e32 v1, v1, v2, vcc
	v_sqrt_f32_e32 v2, v1
	s_nop 0
	v_add_u32_e32 v3, -1, v2
	v_fma_f32 v4, -v3, v2, v1
	v_cmp_ge_f32_e64 s[0:1], 0, v4
	v_add_u32_e32 v4, 1, v2
	s_nop 0
	v_cndmask_b32_e64 v3, v2, v3, s[0:1]
	v_fma_f32 v2, -v4, v2, v1
	v_cmp_lt_f32_e64 s[0:1], 0, v2
	s_nop 1
	v_cndmask_b32_e64 v2, v3, v4, s[0:1]
	v_mul_f32_e32 v3, 0x37800000, v2
	v_cndmask_b32_e32 v2, v2, v3, vcc
	v_cmp_class_f32_e32 vcc, v1, v5
	s_nop 1
	v_cndmask_b32_e32 v1, v2, v1, vcc
	s_nop 0
	v_readfirstlane_b32 s0, v1
	s_nop 1
	v_mul_f32_e32 v214, s0, v6
	v_readfirstlane_b32 s0, v0
	s_bitcmp1_b32 s0, 0
	s_cselect_b64 s[20:21], -1, 0
	s_lshl_b64 s[0:1], s[46:47], 13
	s_add_u32 s0, s30, s0
	s_addc_u32 s1, s31, s1
	s_lshl_b32 s2, s44, 8
	s_add_u32 s52, s0, s2
	s_addc_u32 s53, s1, 0
	s_lshl_b64 s[48:49], s[48:49], 25
	s_add_u32 s0, s30, s48
	s_addc_u32 s1, s31, s49
	s_add_u32 s50, s0, s2
	s_addc_u32 s51, s1, 0
	s_mov_b64 s[0:1], -1
	s_and_b64 vcc, exec, s[20:21]
	s_cbranch_vccz .LBB0_347
	v_readlane_b32 s0, v254, 39
	v_mov_b32_e32 v146, v232
	v_mov_b32_e32 v201, v144
	v_mov_b32_e32 v0, s0
	ds_read_b32 v0, v0
	v_readlane_b32 s0, v254, 40
	v_lshrrev_b32_e32 v2, 1, v146
	v_and_b32_e32 v200, 16, v2
	v_lshlrev_b32_e32 v8, 4, v146
	s_waitcnt lgkmcnt(0)
	v_readfirstlane_b32 s61, v0
	v_mov_b32_e32 v0, s0
	ds_read_b32 v0, v0
	s_movk_i32 s0, 0xffe0
	v_and_b32_e32 v9, 48, v8
	v_ashrrev_i32_e32 v12, 3, v146
	v_ashrrev_i32_e32 v13, 31, v12
	s_waitcnt lgkmcnt(0)
	v_readfirstlane_b32 s62, v0
	v_ashrrev_i32_e32 v0, 1, v146
	v_and_b32_e32 v1, 0xffffffe0, v0
	v_add_u32_e32 v1, s39, v1
	v_bfi_b32 v0, s0, v0, v146
	v_readfirstlane_b32 s63, v1
	v_ashrrev_i32_e32 v1, 31, v0
	v_lshlrev_b64 v[0:1], 13, v[0:1]
	v_lshl_add_u64 v[0:1], s[52:53], 0, v[0:1]
	v_lshl_add_u64 v[0:1], v[0:1], 0, v[200:201]
	global_load_dwordx4 v[164:167], v[0:1], off
	global_load_dwordx4 v[160:163], v[0:1], off offset:32
	global_load_dwordx4 v[156:159], v[0:1], off offset:64
	global_load_dwordx4 v[152:155], v[0:1], off offset:96
	s_barrier
	v_lshlrev_b64 v[52:53], 13, v[12:13]
	v_mov_b32_e32 v11, v144
	v_and_b32_e32 v147, 31, v146
	v_add_u32_e32 v215, s63, v147
	v_ashrrev_i32_e32 v2, 4, v146
	v_and_b32_e32 v3, 0xfffff0, v2
	v_lshlrev_b32_e32 v5, 1, v2
	v_lshlrev_b32_e32 v1, 3, v146
	v_and_or_b32 v3, v5, 8, v3
	v_lshrrev_b32_e32 v5, 1, v2
	v_lshrrev_b32_e32 v3, 1, v3
	v_bfe_u32 v7, v1, 5, 2
	v_and_b32_e32 v6, 3, v2
	v_or_b32_e32 v3, v3, v7
	v_and_or_b32 v5, v5, 4, v6
	v_lshlrev_b32_e32 v3, 9, v3
	v_lshlrev_b32_e32 v5, 6, v5
	v_add_u32_e32 v6, 32, v2
	v_or3_b32 v201, v3, v5, v9
	v_and_b32_e32 v3, 0xfffff0, v6
	v_lshlrev_b32_e32 v10, 1, v6
	v_and_or_b32 v3, v10, 8, v3
	v_lshrrev_b32_e32 v3, 1, v3
	v_or_b32_e32 v3, v3, v7
	v_lshlrev_b32_e32 v3, 9, v3
	v_or3_b32 v217, v3, v5, v9
	v_lshlrev_b32_e32 v3, 7, v12
	v_and_b32_e32 v10, 0x70, v8
	v_and_b32_e32 v5, 0x70, v146
	v_bitop3_b32 v218, v10, v3, v5 bitop3:0xde
	v_ashrrev_i32_e32 v3, 31, v2
	v_and_b32_e32 v4, 0x78, v1
	v_lshlrev_b64 v[50:51], 13, v[2:3]
	v_lshl_add_u64 v[2:3], s[50:51], 0, v[50:51]
	v_lshlrev_b32_e32 v8, 1, v4
	v_mov_b32_e32 v9, v144
	v_ashrrev_i32_e32 v7, 31, v6
	v_lshl_add_u64 v[18:19], v[2:3], 0, v[8:9]
	v_lshlrev_b64 v[6:7], 13, v[6:7]
	global_load_dwordx4 v[2:5], v[18:19], off offset:2048
	v_lshl_add_u64 v[6:7], s[50:51], 0, v[6:7]
	s_mov_b32 s0, 0x80000
	v_lshl_add_u64 v[6:7], v[6:7], 0, v[8:9]
	v_add_co_u32_e32 v14, vcc, s0, v18
	global_load_dwordx4 v[6:9], v[6:7], off offset:2048
	v_lshl_add_u64 v[12:13], s[50:51], 0, v[52:53]
	v_addc_co_u32_e32 v15, vcc, 0, v19, vcc
	s_mov_b32 s1, 0xc0000
	v_lshl_add_u64 v[20:21], v[12:13], 0, v[10:11]
	v_add_co_u32_e32 v22, vcc, s1, v18
	global_load_dwordx4 v[10:13], v[20:21], off offset:1024
	s_nop 0
	v_addc_co_u32_e32 v23, vcc, 0, v19, vcc
	global_load_dwordx4 v[14:17], v[14:15], off offset:2048
	v_add_co_u32_e32 v26, vcc, s0, v20
	global_load_dwordx4 v[22:25], v[22:23], off offset:2048
	s_nop 0
	v_addc_co_u32_e32 v27, vcc, 0, v21, vcc
	global_load_dwordx4 v[26:29], v[26:27], off offset:1024
	s_waitcnt vmcnt(9)
; __device__ __forceinline__ float bf2f(unsigned short b) { return __uint_as_float(((unsigned)b) << 16); }
; __device__ __forceinline__ int v_st(int k, int c) { const int kk = (k & ~0xC) | ((k & 4) << 1) | ((k & 8) >> 1); return ((kk >> 3) * 4 + (c >> 5)) * 512 + ((kk & 7) * 32 + (c & 31)) * 2; }
; __device__ __forceinline__ int v_rd_base(int lane) { return ((lane & 3) << 3) | (((lane >> 2) & 3) << 6) | (((lane >> 4) & 1) << 5) | (((lane >> 5) & 1) << 8); }
; #define SLOAD(i, k0) do { sr_[i].vs0 = *(const GAS bf16x8*)(&Vh[(long)((k0) + sr) * LDK + sc]); sr_[i].vs1 = *(const GAS bf16x8*)(&Vh[(long)((k0) + 32 + sr) * LDK + sc]); \
;     sr_[i].ks0 = *(const GAS bf16x8*)(&Kh[(long)((k0) + kr) * LDK + kc]); } while (0)
; #define SWRITE(b, i) do { *(bf16x8*)(V_lds + (b) * SHM_V + vst0) = sr_[i].vs0; *(bf16x8*)(V_lds + (b) * SHM_V + vst1) = sr_[i].vs1; \
;     *(bf16x8*)(K_lds + (b) * SHM_K + kst) = sr_[i].ks0; } while (0)
; template <bool GRPB> __device__ __forceinline__ void attn_pass(const float mbK, const float bmax2, const int pass, float* __restrict__ scr, bf16* __restrict__ mixrow, const float lam, const float* __restrict__ gsub, const float one_m_li, ...
;     ...
;   { float qs = 0.f;
; #pragma unroll
;     for (int d0 = 0; d0 < 4; ++d0)
; #pragma unroll
;       for (int j = 0; j < 8; ++j) { const float v = bf2f((unsigned short)qr[d0][j]); qs = fmaf(v, v, qs); }
;     { auto rr = __builtin_amdgcn_permlane32_swap(__float_as_uint(qs), __float_as_uint(qs), false, false); qs = __uint_as_float(rr[0]) + __uint_as_float(rr[1]); }
;     m_reg = __builtin_sqrtf(qs) * mbK + bmax2 + 0.25f; }
;   const int sr = tid >> 4, sc = (tid & 15) * 8, vst0 = v_st(sr, sc), vst1 = v_st(32 + sr, sc);
;   const int kr = tid >> 3, kc = (tid & 7) * 8, kst = KSWZ64(kr, kc * 2);
;   const int vb0 = (int)(uintptr_t)V_lds + v_rd_base(lane);
;   struct { bf16x8 vs0, vs1, ks0; } sr_[2];
;     ...
;   f32x16 pA0, pA1, pB0, pB1; float mnA, mnB, alA, alB; bf16x8 pa0, pa1, pa2, pa3; constexpr int NT = SEQ / KVBLK;
;   __syncthreads();
;   SLOAD(0, 0); SLOAD(1, KVBLK); asm volatile("s_waitcnt vmcnt(0)" ::: "memory"); SWRITE(0, 0); SWRITE(1, 1);
;   SLOAD(0, 2 * KVBLK); asm volatile("s_waitcnt vmcnt(0)" ::: "memory"); SWRITE(2, 0); __syncthreads();
	v_lshlrev_b32_e32 v103, 16, v164
	v_fma_f32 v103, v103, v103, 0
	v_and_b32_e32 v100, 0xffff0000, v164
	v_fmac_f32_e32 v103, v100, v100
	v_lshlrev_b32_e32 v100, 16, v165
	v_fmac_f32_e32 v103, v100, v100
	v_and_b32_e32 v100, 0xffff0000, v165
	v_fmac_f32_e32 v103, v100, v100
	v_lshlrev_b32_e32 v100, 16, v166
	v_fmac_f32_e32 v103, v100, v100
	v_and_b32_e32 v100, 0xffff0000, v166
	v_fmac_f32_e32 v103, v100, v100
	v_lshlrev_b32_e32 v100, 16, v167
	v_fmac_f32_e32 v103, v100, v100
	v_and_b32_e32 v100, 0xffff0000, v167
	v_fmac_f32_e32 v103, v100, v100
	s_waitcnt vmcnt(8)
	v_lshlrev_b32_e32 v100, 16, v160
	v_fmac_f32_e32 v103, v100, v100
	v_and_b32_e32 v100, 0xffff0000, v160
	v_fmac_f32_e32 v103, v100, v100
	v_lshlrev_b32_e32 v100, 16, v161
	v_fmac_f32_e32 v103, v100, v100
	v_and_b32_e32 v100, 0xffff0000, v161
	v_fmac_f32_e32 v103, v100, v100
	v_lshlrev_b32_e32 v100, 16, v162
	v_fmac_f32_e32 v103, v100, v100
	v_and_b32_e32 v100, 0xffff0000, v162
	v_fmac_f32_e32 v103, v100, v100
	v_lshlrev_b32_e32 v100, 16, v163
	v_fmac_f32_e32 v103, v100, v100
	v_and_b32_e32 v100, 0xffff0000, v163
	v_fmac_f32_e32 v103, v100, v100
	s_waitcnt vmcnt(7)
	v_lshlrev_b32_e32 v100, 16, v156
	v_fmac_f32_e32 v103, v100, v100
	v_and_b32_e32 v100, 0xffff0000, v156
	v_fmac_f32_e32 v103, v100, v100
	v_lshlrev_b32_e32 v100, 16, v157
	v_fmac_f32_e32 v103, v100, v100
	v_and_b32_e32 v100, 0xffff0000, v157
	v_fmac_f32_e32 v103, v100, v100
	v_lshlrev_b32_e32 v100, 16, v158
	v_fmac_f32_e32 v103, v100, v100
	v_and_b32_e32 v100, 0xffff0000, v158
	v_fmac_f32_e32 v103, v100, v100
	v_lshlrev_b32_e32 v100, 16, v159
	v_fmac_f32_e32 v103, v100, v100
	v_and_b32_e32 v100, 0xffff0000, v159
	v_fmac_f32_e32 v103, v100, v100
	s_waitcnt vmcnt(6)
	v_lshlrev_b32_e32 v100, 16, v152
	v_fmac_f32_e32 v103, v100, v100
	v_and_b32_e32 v100, 0xffff0000, v152
	v_fmac_f32_e32 v103, v100, v100
	v_lshlrev_b32_e32 v100, 16, v153
	v_fmac_f32_e32 v103, v100, v100
	v_and_b32_e32 v100, 0xffff0000, v153
	v_fmac_f32_e32 v103, v100, v100
	v_lshlrev_b32_e32 v100, 16, v154
	v_fmac_f32_e32 v103, v100, v100
	v_and_b32_e32 v100, 0xffff0000, v154
	v_fmac_f32_e32 v103, v100, v100
	v_lshlrev_b32_e32 v100, 16, v155
	v_fmac_f32_e32 v103, v100, v100
	v_and_b32_e32 v100, 0xffff0000, v155
	v_fmac_f32_e32 v103, v100, v100
	v_mov_b32_e32 v100, v103
	s_nop 1
	v_permlane32_swap_b32_e32 v103, v100
	v_add_f32_e32 v103, v103, v100
	v_cmp_gt_f32_e32 vcc, s10, v103
	v_mul_f32_e32 v100, 0x4f800000, v103
	s_nop 0
	v_cndmask_b32_e32 v103, v103, v100, vcc
	v_sqrt_f32_e32 v100, v103
	s_nop 0
	v_add_u32_e32 v101, -1, v100
	v_fma_f32 v102, -v101, v100, v103
	v_cmp_ge_f32_e64 s[0:1], 0, v102
	v_add_u32_e32 v102, 1, v100
	s_nop 0
	v_cndmask_b32_e64 v101, v100, v101, s[0:1]
	v_fma_f32 v100, -v102, v100, v103
	v_cmp_lt_f32_e64 s[0:1], 0, v100
	s_nop 1
	v_cndmask_b32_e64 v100, v101, v102, s[0:1]
	v_mul_f32_e32 v101, 0x37800000, v100
	v_cndmask_b32_e32 v100, v100, v101, vcc
	v_cmp_class_f32_e32 vcc, v103, v198
	v_cndmask_b32_e32 v103, v100, v103, vcc
	v_mov_b32_e32 v0, v103
	v_add_u32_e32 v30, 0, v201
	s_mov_b32 s0, 0x100000
	s_waitcnt vmcnt(0)
	v_add_u32_e32 v31, 0, v217
	s_mov_b32 s1, 0x140000
	v_add_u32_e32 v222, 0, v218
	v_and_b32_e32 v1, 0x70, v1
	v_fma_f32 v0, v216, v0, s45
	v_add_f32_e32 v0, 0x3e800000, v0
	s_waitcnt vmcnt(5)
	ds_write_b128 v30, v[2:5]
	v_add_co_u32_e32 v2, vcc, s0, v18
	s_waitcnt vmcnt(4)
	ds_write_b128 v31, v[6:9]
	v_addc_co_u32_e32 v3, vcc, 0, v19, vcc
	v_add_co_u32_e32 v6, vcc, s1, v18
	s_waitcnt vmcnt(3)
	ds_write_b128 v222, v[10:13] offset:49152
	s_waitcnt vmcnt(2)
	ds_write_b128 v30, v[14:17] offset:16384
	s_waitcnt vmcnt(1)
	ds_write_b128 v31, v[22:25] offset:16384
	s_waitcnt vmcnt(0)
	ds_write_b128 v222, v[26:29] offset:57344
	v_addc_co_u32_e32 v7, vcc, 0, v19, vcc
	v_add_co_u32_e32 v10, vcc, s0, v20
	global_load_dwordx4 v[2:5], v[2:3], off offset:2048
	s_nop 0
	v_addc_co_u32_e32 v11, vcc, 0, v21, vcc
	global_load_dwordx4 v[6:9], v[6:7], off offset:2048
	s_nop 0
	global_load_dwordx4 v[10:13], v[10:11], off offset:1024
	s_waitcnt vmcnt(0)
	s_waitcnt vmcnt(2)
	ds_write_b128 v30, v[2:5] offset:32768
	s_waitcnt vmcnt(1)
	ds_write_b128 v31, v[6:9] offset:32768
	v_add_u32_e32 v2, 0x10000, v222
	s_waitcnt vmcnt(0)
	ds_write_b128 v2, v[10:13]
	v_lshlrev_b32_e32 v10, 7, v147
	v_or_b32_e32 v11, 32, v200
	v_bitop3_b32 v227, v11, v10, v1 bitop3:0xde
	v_or_b32_e32 v11, 64, v200
	v_bitop3_b32 v229, v11, v10, v1 bitop3:0xde
	v_or_b32_e32 v11, 0x60, v200
	v_bitop3_b32 v224, v200, v10, v1 bitop3:0xde
	v_bitop3_b32 v230, v11, v10, v1 bitop3:0xde
	v_add_u32_e32 v223, 0, v224
	v_add_u32_e32 v225, 0, v227
	v_add_u32_e32 v226, 0, v229
	v_add_u32_e32 v228, 0, v230
	s_waitcnt lgkmcnt(0)
	s_barrier
; #define SBAR() __builtin_amdgcn_sched_barrier(0)
; __device__ __forceinline__ void partialSM(f32x16& p0, f32x16& p1, float& m_reg, float& mn, float& alpha, int kt0, int qpos, int qw, int hi, const float* tb2, float cL, float cR) {
;   mn = m_reg; alpha = 1.f;
;   const int rel_hi = kt0 + 63 - qw, rel_lo = kt0 - (qw + 31);
;   if (rel_hi <= -91 || rel_lo >= 91) {
;     const float cm = ((rel_hi <= -91) ? cL : cR) - m_reg;
; #pragma unroll
;     for (int r = 0; r < 16; ++r) { p0[r] = fmaf(p0[r], C1, cm); p1[r] = fmaf(p1[r], C1, cm); }
;   } else {
;     const float* tp = tb2 + (kt0 - qpos + 192 + 4 * hi);
; #pragma unroll
;     for (int r4 = 0; r4 < 4; ++r4) {
;       float ta[4], tb[4];
; #pragma unroll
;       for (int i = 0; i < 4; ++i) { ta[i] = tp[8 * r4 + i] - m_reg; tb[i] = tp[32 + 8 * r4 + i] - m_reg; }
; #pragma unroll
;       for (int i = 0; i < 4; ++i) { p0[4 * r4 + i] = fmaf(p0[4 * r4 + i], C1, ta[i]); p1[4 * r4 + i] = fmaf(p1[4 * r4 + i], C1, tb[i]); }
; __device__ __forceinline__ void qkt(f32x16& p0, f32x16& p1, const char* Ks, const bf16x8* qr, int r32, int hi) {
;   bf16x8 ka[4], kb[4];
; #pragma unroll
;   for (int d0 = 0; d0 < 4; ++d0) { const int cb = (d0 * 16 + hi * 8) * 2;
;     ka[d0] = *reinterpret_cast<const bf16x8*>(Ks + KSWZ64(r32, cb)); kb[d0] = *reinterpret_cast<const bf16x8*>(Ks + KSWZ64(32 + r32, cb)); }
;   asm volatile("s_waitcnt lgkmcnt(0)" ::: "memory"); SBAR();
;   p0 = f32x16{}; p1 = f32x16{};
; #pragma unroll
;   for (int d0 = 0; d0 < 4; ++d0) {
;     p0 = __builtin_amdgcn_mfma_f32_32x32x16_bf16(ka[d0], qr[d0], p0, 0, 0, 0);
;     p1 = __builtin_amdgcn_mfma_f32_32x32x16_bf16(kb[d0], qr[d0], p1, 0, 0, 0); }
; }
	ds_read_b128 v[2:5], v223 offset:49152
	ds_read_b128 v[6:9], v223 offset:53248
	ds_read_b128 v[34:37], v225 offset:49152
	ds_read_b128 v[38:41], v225 offset:53248
	ds_read_b128 v[42:45], v226 offset:49152
	ds_read_b128 v[46:49], v226 offset:53248
	ds_read_b128 v[54:57], v228 offset:49152
	ds_read_b128 v[58:61], v228 offset:53248
	s_waitcnt lgkmcnt(0)
	s_waitcnt lgkmcnt(7)
	v_mfma_f32_32x32x16_bf16 v[18:33], v[2:5], v[164:167], 0
	s_add_i32 s2, s63, 0xffffff66
	s_mov_b64 s[0:1], -1
	s_cmp_gt_u32 s2, 0xfffffeec
	s_waitcnt lgkmcnt(6)
	v_mfma_f32_32x32x16_bf16 v[2:17], v[6:9], v[164:167], 0
	s_waitcnt lgkmcnt(5)
	v_mfma_f32_32x32x16_bf16 v[18:33], v[34:37], v[160:163], v[18:33]
	s_waitcnt lgkmcnt(4)
	v_mfma_f32_32x32x16_bf16 v[2:17], v[38:41], v[160:163], v[2:17]
	s_waitcnt lgkmcnt(3)
	v_mfma_f32_32x32x16_bf16 v[18:33], v[42:45], v[156:159], v[18:33]
	s_waitcnt lgkmcnt(2)
	v_mfma_f32_32x32x16_bf16 v[2:17], v[46:49], v[156:159], v[2:17]
	s_waitcnt lgkmcnt(1)
	v_mfma_f32_32x32x16_bf16 v[18:33], v[54:57], v[152:155], v[18:33]
	v_lshlrev_b32_e32 v54, 2, v215
	s_waitcnt lgkmcnt(0)
	v_mfma_f32_32x32x16_bf16 v[2:17], v[58:61], v[152:155], v[2:17]
	s_cbranch_scc0 .LBB0_298
	v_sub_u32_e32 v1, 0, v54
	s_mov_b32 s0, 0x12b00
	v_add3_u32 v1, v1, v200, s0
	ds_read2_b32 v[34:35], v1 offset1:1
	ds_read2_b32 v[56:57], v1 offset0:32 offset1:33
	ds_read2_b32 v[58:59], v1 offset0:34 offset1:35
	ds_read2_b32 v[36:37], v1 offset0:2 offset1:3
	ds_read2_b32 v[38:39], v1 offset0:8 offset1:9
	ds_read2_b32 v[60:61], v1 offset0:40 offset1:41
	ds_read2_b32 v[62:63], v1 offset0:42 offset1:43
	ds_read2_b32 v[40:41], v1 offset0:10 offset1:11
	ds_read2_b32 v[42:43], v1 offset0:16 offset1:17
	ds_read2_b32 v[64:65], v1 offset0:48 offset1:49
	ds_read2_b32 v[66:67], v1 offset0:50 offset1:51
	ds_read2_b32 v[44:45], v1 offset0:18 offset1:19
	ds_read2_b32 v[46:47], v1 offset0:24 offset1:25
	ds_read2_b32 v[48:49], v1 offset0:26 offset1:27
	ds_read2_b32 v[68:69], v1 offset0:58 offset1:59
	ds_read2_b32 v[70:71], v1 offset0:56 offset1:57
	s_waitcnt lgkmcnt(3)
	v_sub_f32_e32 v47, v47, v0
	v_sub_f32_e32 v46, v46, v0
	s_waitcnt lgkmcnt(2)
	v_sub_f32_e32 v49, v49, v0
	v_sub_f32_e32 v48, v48, v0
	v_sub_f32_e32 v43, v43, v0
	v_sub_f32_e32 v42, v42, v0
	v_sub_f32_e32 v45, v45, v0
	v_sub_f32_e32 v44, v44, v0
	v_sub_f32_e32 v39, v39, v0
	v_sub_f32_e32 v38, v38, v0
	v_sub_f32_e32 v41, v41, v0
	v_sub_f32_e32 v40, v40, v0
	v_sub_f32_e32 v35, v35, v0
	v_sub_f32_e32 v34, v34, v0
	v_sub_f32_e32 v37, v37, v0
	v_sub_f32_e32 v36, v36, v0
	s_waitcnt lgkmcnt(0)
	v_sub_f32_e32 v71, v71, v0
	v_sub_f32_e32 v70, v70, v0
	v_sub_f32_e32 v69, v69, v0
	v_sub_f32_e32 v68, v68, v0
	v_sub_f32_e32 v65, v65, v0
	v_sub_f32_e32 v64, v64, v0
	v_sub_f32_e32 v67, v67, v0
	v_sub_f32_e32 v66, v66, v0
	v_sub_f32_e32 v61, v61, v0
	v_sub_f32_e32 v60, v60, v0
	v_sub_f32_e32 v63, v63, v0
	v_sub_f32_e32 v62, v62, v0
	v_sub_f32_e32 v57, v57, v0
	v_sub_f32_e32 v56, v56, v0
	v_sub_f32_e32 v59, v59, v0
	v_sub_f32_e32 v58, v58, v0
	v_pk_fma_f32 v[36:37], v[20:21], s[6:7], v[36:37] op_sel_hi:[1,0,1]
	v_pk_fma_f32 v[34:35], v[18:19], s[6:7], v[34:35] op_sel_hi:[1,0,1]
	v_pk_fma_f32 v[40:41], v[24:25], s[6:7], v[40:41] op_sel_hi:[1,0,1]
	v_pk_fma_f32 v[38:39], v[22:23], s[6:7], v[38:39] op_sel_hi:[1,0,1]
	v_pk_fma_f32 v[44:45], v[28:29], s[6:7], v[44:45] op_sel_hi:[1,0,1]
	v_pk_fma_f32 v[42:43], v[26:27], s[6:7], v[42:43] op_sel_hi:[1,0,1]
	v_pk_fma_f32 v[48:49], v[32:33], s[6:7], v[48:49] op_sel_hi:[1,0,1]
	v_pk_fma_f32 v[46:47], v[30:31], s[6:7], v[46:47] op_sel_hi:[1,0,1]
	v_pk_fma_f32 v[82:83], v[4:5], s[6:7], v[58:59] op_sel_hi:[1,0,1]
	v_pk_fma_f32 v[80:81], v[2:3], s[6:7], v[56:57] op_sel_hi:[1,0,1]
	v_pk_fma_f32 v[86:87], v[8:9], s[6:7], v[62:63] op_sel_hi:[1,0,1]
	v_pk_fma_f32 v[84:85], v[6:7], s[6:7], v[60:61] op_sel_hi:[1,0,1]
	v_pk_fma_f32 v[90:91], v[12:13], s[6:7], v[66:67] op_sel_hi:[1,0,1]
	v_pk_fma_f32 v[88:89], v[10:11], s[6:7], v[64:65] op_sel_hi:[1,0,1]
	v_pk_fma_f32 v[94:95], v[16:17], s[6:7], v[68:69] op_sel_hi:[1,0,1]
	v_pk_fma_f32 v[92:93], v[14:15], s[6:7], v[70:71] op_sel_hi:[1,0,1]
	s_mov_b64 s[0:1], 0

; #define GAS __attribute__((address_space(1)))
; __device__ __forceinline__ float bf2f(unsigned short b) { return __uint_as_float(((unsigned)b) << 16); }
; template <bool GRPB> __device__ __forceinline__ void attn_pass(const float mbK, const float bmax2, const int pass, float* __restrict__ scr, bf16* __restrict__ mixrow, const float lam, const float* __restrict__ gsub, const float one_m_li, ...
;     ...
;   const float cL = __uint_as_float(__builtin_amdgcn_readfirstlane(__float_as_uint(tb2[0]))), cR = __uint_as_float(__builtin_amdgcn_readfirstlane(__float_as_uint(tb2[384])));
;   const int qw = __builtin_amdgcn_readfirstlane(q0seq + wid * 32), qpos = qw + r32;
;   float m_reg, l_reg = 0; bf16x8 qr[4]; f32x16 o[4];
; #pragma unroll
;   for (int d = 0; d < 4; ++d) o[d] = f32x16{};
;   const bf16* Qw = Qb + (long)(wid * 32 + r32) * LDK + hi * 8;
; #pragma unroll
;   for (int d0 = 0; d0 < 4; ++d0) qr[d0] = *(const GAS bf16x8*)(Qw + d0 * 16);
;   { float qs = 0.f;
; #pragma unroll
;     for (int d0 = 0; d0 < 4; ++d0)
; #pragma unroll
;       for (int j = 0; j < 8; ++j) { const float v = bf2f((unsigned short)qr[d0][j]); qs = fmaf(v, v, qs); }
;     { auto rr = __builtin_amdgcn_permlane32_swap(__float_as_uint(qs), __float_as_uint(qs), false, false); qs = __uint_as_float(rr[0]) + __uint_as_float(rr[1]); }
;     m_reg = __builtin_sqrtf(qs) * mbK + bmax2 + 0.25f; }
;   const int sr = tid >> 4, sc = (tid & 15) * 8, vst0 = v_st(sr, sc), vst1 = v_st(32 + sr, sc);
;   const int kr = tid >> 3, kc = (tid & 7) * 8, kst = KSWZ64(kr, kc * 2);
;   const int vb0 = (int)(uintptr_t)V_lds + v_rd_base(lane);
;   struct { bf16x8 vs0, vs1, ks0; } sr_[2];
;     ...
;   f32x16 pA0, pA1, pB0, pB1; float mnA, mnB, alA, alB; bf16x8 pa0, pa1, pa2, pa3; constexpr int NT = SEQ / KVBLK;
;   __syncthreads();
;   SLOAD(0, 0); SLOAD(1, KVBLK); asm volatile("s_waitcnt vmcnt(0)" ::: "memory"); SWRITE(0, 0); SWRITE(1, 1);
;     ...
;   if (pass == 0) {
; #pragma unroll
;     for (int r4 = 0; r4 < 4; ++r4) { const f32x4 lv = *(const f32x4*)(li_e + 8 * r4 + 4 * hi);
;       const f32x4 rl = (f32x4){__builtin_amdgcn_rcpf(lv[0]), __builtin_amdgcn_rcpf(lv[1]), __builtin_amdgcn_rcpf(lv[2]), __builtin_amdgcn_rcpf(lv[3])};
; #pragma unroll
;       for (int d0 = 0; d0 < 4; ++d0) scr4[d0 * 4 + r4] = (f32x4){o[d0][4 * r4 + 0] * rl[0], o[d0][4 * r4 + 1] * rl[1], o[d0][4 * r4 + 2] * rl[2], o[d0][4 * r4 + 3] * rl[3]}; }
.LBB0_321:
	s_or_b64 exec, exec, s[0:1]
	s_waitcnt lgkmcnt(0)
	v_add_u32_e32 v74, v66, v200
	ds_read_b128 v[66:69], v74
	ds_read_b128 v[70:73], v74 offset:32
	v_ashrrev_i32_e32 v147, 31, v146
	v_lshlrev_b64 v[0:1], 8, v[146:147]
	v_lshl_add_u64 v[0:1], s[40:41], 0, v[0:1]
	s_waitcnt lgkmcnt(1)
	v_rcp_f32_e32 v66, v66
	v_rcp_f32_e32 v67, v67
	v_rcp_f32_e32 v68, v68
	v_rcp_f32_e32 v69, v69
	v_readlane_b32 s0, v254, 39
	v_pk_mul_f32 v[2:3], v[2:3], v[66:67]
	v_mov_b32_e32 v146, v232
	v_pk_mul_f32 v[4:5], v[4:5], v[68:69]
	global_store_dwordx4 v[0:1], v[2:5], off
	v_mov_b32_e32 v201, v144
	s_nop 0
	v_pk_mul_f32 v[2:3], v[18:19], v[66:67]
	v_pk_mul_f32 v[4:5], v[20:21], v[68:69]
	s_waitcnt lgkmcnt(0)
	v_rcp_f32_e32 v18, v70
	v_rcp_f32_e32 v19, v71
	v_rcp_f32_e32 v20, v72
	v_rcp_f32_e32 v21, v73
	global_store_dwordx4 v[0:1], v[2:5], off offset:64
	s_nop 1
	v_pk_mul_f32 v[2:3], v[34:35], v[66:67]
	v_pk_mul_f32 v[4:5], v[36:37], v[68:69]
	global_store_dwordx4 v[0:1], v[2:5], off offset:128
	s_nop 1
	v_pk_mul_f32 v[2:3], v[50:51], v[66:67]
	v_pk_mul_f32 v[4:5], v[52:53], v[68:69]
	global_store_dwordx4 v[0:1], v[2:5], off offset:192
	s_nop 1
	v_pk_mul_f32 v[2:3], v[6:7], v[18:19]
	v_pk_mul_f32 v[4:5], v[8:9], v[20:21]
	global_store_dwordx4 v[0:1], v[2:5], off offset:16
	s_nop 1
	v_pk_mul_f32 v[2:3], v[22:23], v[18:19]
	v_pk_mul_f32 v[4:5], v[24:25], v[20:21]
	global_store_dwordx4 v[0:1], v[2:5], off offset:80
	s_nop 1
	v_pk_mul_f32 v[2:3], v[38:39], v[18:19]
	v_pk_mul_f32 v[4:5], v[40:41], v[20:21]
	global_store_dwordx4 v[0:1], v[2:5], off offset:144
	s_nop 1
	v_pk_mul_f32 v[2:3], v[54:55], v[18:19]
	v_pk_mul_f32 v[4:5], v[56:57], v[20:21]
	global_store_dwordx4 v[0:1], v[2:5], off offset:208
	ds_read_b128 v[2:5], v74 offset:64
	s_waitcnt lgkmcnt(0)
	v_rcp_f32_e32 v6, v2
	v_rcp_f32_e32 v7, v3
	v_rcp_f32_e32 v8, v4
	v_rcp_f32_e32 v9, v5
	v_pk_mul_f32 v[2:3], v[10:11], v[6:7]
	v_mov_b32_e32 v11, v144
	v_pk_mul_f32 v[4:5], v[12:13], v[8:9]
	global_store_dwordx4 v[0:1], v[2:5], off offset:32
	s_nop 1
	v_pk_mul_f32 v[2:3], v[26:27], v[6:7]
	v_pk_mul_f32 v[4:5], v[28:29], v[8:9]
	global_store_dwordx4 v[0:1], v[2:5], off offset:96
	s_nop 1
	v_pk_mul_f32 v[2:3], v[42:43], v[6:7]
	v_pk_mul_f32 v[4:5], v[44:45], v[8:9]
	global_store_dwordx4 v[0:1], v[2:5], off offset:160
	s_nop 1
	v_pk_mul_f32 v[2:3], v[58:59], v[6:7]
	v_pk_mul_f32 v[4:5], v[60:61], v[8:9]
	global_store_dwordx4 v[0:1], v[2:5], off offset:224
	ds_read_b128 v[2:5], v74 offset:96
	s_waitcnt lgkmcnt(0)
	v_rcp_f32_e32 v6, v2
	v_rcp_f32_e32 v7, v3
	v_rcp_f32_e32 v8, v4
	v_rcp_f32_e32 v9, v5
	v_pk_mul_f32 v[2:3], v[14:15], v[6:7]
	v_pk_mul_f32 v[4:5], v[16:17], v[8:9]
	global_store_dwordx4 v[0:1], v[2:5], off offset:48
	s_nop 1
	v_pk_mul_f32 v[2:3], v[30:31], v[6:7]
	v_pk_mul_f32 v[4:5], v[32:33], v[8:9]
	global_store_dwordx4 v[0:1], v[2:5], off offset:112
	s_nop 1
	v_pk_mul_f32 v[2:3], v[46:47], v[6:7]
	v_pk_mul_f32 v[4:5], v[48:49], v[8:9]
	global_store_dwordx4 v[0:1], v[2:5], off offset:176
	s_nop 1
	v_pk_mul_f32 v[2:3], v[62:63], v[6:7]
	v_pk_mul_f32 v[4:5], v[64:65], v[8:9]
	global_store_dwordx4 v[0:1], v[2:5], off offset:240
	v_mov_b32_e32 v0, s0
	ds_read_b32 v0, v0
	v_readlane_b32 s0, v254, 40
	v_bfe_u32 v217, v146, 5, 1
	v_lshlrev_b32_e32 v200, 4, v217
	v_lshlrev_b32_e32 v12, 3, v146
	s_waitcnt lgkmcnt(0)
	v_readfirstlane_b32 s62, v0
	v_mov_b32_e32 v0, s0
	ds_read_b32 v0, v0
	s_movk_i32 s0, 0xffe0
	v_bfe_u32 v5, v12, 5, 2
	v_lshlrev_b32_e32 v6, 4, v146
	v_and_b32_e32 v7, 48, v6
	s_waitcnt lgkmcnt(0)
	v_readfirstlane_b32 s63, v0
	v_ashrrev_i32_e32 v0, 1, v146
	v_and_b32_e32 v215, 0xffffffe0, v0
	v_add_u32_e32 v1, s39, v215
	v_bfi_b32 v0, s0, v0, v146
	v_readfirstlane_b32 s64, v1
	v_ashrrev_i32_e32 v1, 31, v0
	v_lshlrev_b64 v[0:1], 13, v[0:1]
	v_lshl_add_u64 v[0:1], s[52:53], 0, v[0:1]
	v_lshl_add_u64 v[0:1], v[0:1], 0, v[200:201]
	global_load_dwordx4 v[164:167], v[0:1], off offset:128
	global_load_dwordx4 v[160:163], v[0:1], off offset:160
	global_load_dwordx4 v[152:155], v[0:1], off offset:192
	global_load_dwordx4 v[156:159], v[0:1], off offset:224
	v_and_b32_e32 v10, 0x70, v6
	s_barrier
	v_and_b32_e32 v218, 31, v146
	v_add_u32_e32 v147, s64, v218
	v_and_b32_e32 v2, 0x78, v12
	v_lshlrev_b32_e32 v6, 1, v2
	v_ashrrev_i32_e32 v0, 4, v146
	v_and_b32_e32 v1, 0xfffff0, v0
	v_lshlrev_b32_e32 v3, 1, v0
	v_and_or_b32 v1, v3, 8, v1
	v_lshrrev_b32_e32 v3, 1, v0
	v_lshrrev_b32_e32 v1, 1, v1
	v_and_b32_e32 v4, 3, v0
	v_or_b32_e32 v1, v1, v5
	v_and_or_b32 v3, v3, 4, v4
	v_lshlrev_b32_e32 v1, 9, v1
	v_lshlrev_b32_e32 v3, 6, v3
	v_add_u32_e32 v4, 32, v0
	v_or3_b32 v221, v1, v3, v7
	v_and_b32_e32 v1, 0xfffff0, v4
	v_lshlrev_b32_e32 v8, 1, v4
	v_and_or_b32 v1, v8, 8, v1
	v_lshrrev_b32_e32 v1, 1, v1
	v_or_b32_e32 v1, v1, v5
	v_lshlrev_b32_e32 v1, 9, v1
	v_ashrrev_i32_e32 v8, 3, v146
	v_or3_b32 v222, v1, v3, v7
	v_lshlrev_b32_e32 v1, 7, v8
	v_and_b32_e32 v3, 0x70, v146
	v_bitop3_b32 v223, v10, v1, v3 bitop3:0xde
	v_ashrrev_i32_e32 v1, 31, v0
	v_lshlrev_b64 v[48:49], 13, v[0:1]
	v_lshl_add_u64 v[0:1], s[50:51], 0, v[48:49]
	v_mov_b32_e32 v7, v144
	v_ashrrev_i32_e32 v5, 31, v4
	v_lshl_add_u64 v[26:27], v[0:1], 0, v[6:7]
	v_lshlrev_b64 v[4:5], 13, v[4:5]
	global_load_dwordx4 v[0:3], v[26:27], off offset:2048
	v_lshl_add_u64 v[4:5], s[50:51], 0, v[4:5]
	v_ashrrev_i32_e32 v9, 31, v8
	s_mov_b32 s0, 0x80000
	v_lshl_add_u64 v[4:5], v[4:5], 0, v[6:7]
	v_lshlrev_b64 v[50:51], 13, v[8:9]
	v_add_co_u32_e32 v14, vcc, s0, v26
	global_load_dwordx4 v[4:7], v[4:5], off offset:2048
	v_lshl_add_u64 v[8:9], s[50:51], 0, v[50:51]
	v_addc_co_u32_e32 v15, vcc, 0, v27, vcc
	s_mov_b32 s1, 0xc0000
	v_lshl_add_u64 v[28:29], v[8:9], 0, v[10:11]
	v_add_co_u32_e32 v18, vcc, s1, v26
	global_load_dwordx4 v[8:11], v[28:29], off offset:1152
	s_nop 0
	v_addc_co_u32_e32 v19, vcc, 0, v27, vcc
	global_load_dwordx4 v[14:17], v[14:15], off offset:2048
	v_add_co_u32_e32 v22, vcc, s0, v28
	global_load_dwordx4 v[18:21], v[18:19], off offset:2048
	s_nop 0
	v_addc_co_u32_e32 v23, vcc, 0, v29, vcc
	global_load_dwordx4 v[22:25], v[22:23], off offset:1152
	s_waitcnt vmcnt(9)
; __device__ __forceinline__ float bf2f(unsigned short b) { return __uint_as_float(((unsigned)b) << 16); }
; __device__ __forceinline__ int v_st(int k, int c) { const int kk = (k & ~0xC) | ((k & 4) << 1) | ((k & 8) >> 1); return ((kk >> 3) * 4 + (c >> 5)) * 512 + ((kk & 7) * 32 + (c & 31)) * 2; }
; __device__ __forceinline__ int v_rd_base(int lane) { return ((lane & 3) << 3) | (((lane >> 2) & 3) << 6) | (((lane >> 4) & 1) << 5) | (((lane >> 5) & 1) << 8); }
; #define SLOAD(i, k0) do { sr_[i].vs0 = *(const GAS bf16x8*)(&Vh[(long)((k0) + sr) * LDK + sc]); sr_[i].vs1 = *(const GAS bf16x8*)(&Vh[(long)((k0) + 32 + sr) * LDK + sc]); \
;     sr_[i].ks0 = *(const GAS bf16x8*)(&Kh[(long)((k0) + kr) * LDK + kc]); } while (0)
; #define SWRITE(b, i) do { *(bf16x8*)(V_lds + (b) * SHM_V + vst0) = sr_[i].vs0; *(bf16x8*)(V_lds + (b) * SHM_V + vst1) = sr_[i].vs1; \
;     *(bf16x8*)(K_lds + (b) * SHM_K + kst) = sr_[i].ks0; } while (0)
; template <bool GRPB> __device__ __forceinline__ void attn_pass(const float mbK, const float bmax2, const int pass, float* __restrict__ scr, bf16* __restrict__ mixrow, const float lam, const float* __restrict__ gsub, const float one_m_li, ...
;     ...
;   { float qs = 0.f;
; #pragma unroll
;     for (int d0 = 0; d0 < 4; ++d0)
; #pragma unroll
;       for (int j = 0; j < 8; ++j) { const float v = bf2f((unsigned short)qr[d0][j]); qs = fmaf(v, v, qs); }
;     { auto rr = __builtin_amdgcn_permlane32_swap(__float_as_uint(qs), __float_as_uint(qs), false, false); qs = __uint_as_float(rr[0]) + __uint_as_float(rr[1]); }
;     m_reg = __builtin_sqrtf(qs) * mbK + bmax2 + 0.25f; }
;   const int sr = tid >> 4, sc = (tid & 15) * 8, vst0 = v_st(sr, sc), vst1 = v_st(32 + sr, sc);
;   const int kr = tid >> 3, kc = (tid & 7) * 8, kst = KSWZ64(kr, kc * 2);
;   const int vb0 = (int)(uintptr_t)V_lds + v_rd_base(lane);
;   struct { bf16x8 vs0, vs1, ks0; } sr_[2];
;     ...
;   f32x16 pA0, pA1, pB0, pB1; float mnA, mnB, alA, alB; bf16x8 pa0, pa1, pa2, pa3; constexpr int NT = SEQ / KVBLK;
;   __syncthreads();
;   SLOAD(0, 0); SLOAD(1, KVBLK); asm volatile("s_waitcnt vmcnt(0)" ::: "memory"); SWRITE(0, 0); SWRITE(1, 1);
;   SLOAD(0, 2 * KVBLK); asm volatile("s_waitcnt vmcnt(0)" ::: "memory"); SWRITE(2, 0); __syncthreads();
	v_lshlrev_b32_e32 v103, 16, v164
	v_fma_f32 v103, v103, v103, 0
	v_and_b32_e32 v100, 0xffff0000, v164
	v_fmac_f32_e32 v103, v100, v100
	v_lshlrev_b32_e32 v100, 16, v165
	v_fmac_f32_e32 v103, v100, v100
	v_and_b32_e32 v100, 0xffff0000, v165
	v_fmac_f32_e32 v103, v100, v100
	v_lshlrev_b32_e32 v100, 16, v166
	v_fmac_f32_e32 v103, v100, v100
	v_and_b32_e32 v100, 0xffff0000, v166
	v_fmac_f32_e32 v103, v100, v100
	v_lshlrev_b32_e32 v100, 16, v167
	v_fmac_f32_e32 v103, v100, v100
	v_and_b32_e32 v100, 0xffff0000, v167
	v_fmac_f32_e32 v103, v100, v100
	s_waitcnt vmcnt(8)
	v_lshlrev_b32_e32 v100, 16, v160
	v_fmac_f32_e32 v103, v100, v100
	v_and_b32_e32 v100, 0xffff0000, v160
	v_fmac_f32_e32 v103, v100, v100
	v_lshlrev_b32_e32 v100, 16, v161
	v_fmac_f32_e32 v103, v100, v100
	v_and_b32_e32 v100, 0xffff0000, v161
	v_fmac_f32_e32 v103, v100, v100
	v_lshlrev_b32_e32 v100, 16, v162
	v_fmac_f32_e32 v103, v100, v100
	v_and_b32_e32 v100, 0xffff0000, v162
	v_fmac_f32_e32 v103, v100, v100
	v_lshlrev_b32_e32 v100, 16, v163
	v_fmac_f32_e32 v103, v100, v100
	v_and_b32_e32 v100, 0xffff0000, v163
	v_fmac_f32_e32 v103, v100, v100
	s_waitcnt vmcnt(7)
	v_lshlrev_b32_e32 v100, 16, v152
	v_fmac_f32_e32 v103, v100, v100
	v_and_b32_e32 v100, 0xffff0000, v152
	v_fmac_f32_e32 v103, v100, v100
	v_lshlrev_b32_e32 v100, 16, v153
	v_fmac_f32_e32 v103, v100, v100
	v_and_b32_e32 v100, 0xffff0000, v153
	v_fmac_f32_e32 v103, v100, v100
	v_lshlrev_b32_e32 v100, 16, v154
	v_fmac_f32_e32 v103, v100, v100
	v_and_b32_e32 v100, 0xffff0000, v154
	v_fmac_f32_e32 v103, v100, v100
	v_lshlrev_b32_e32 v100, 16, v155
	v_fmac_f32_e32 v103, v100, v100
	v_and_b32_e32 v100, 0xffff0000, v155
	v_fmac_f32_e32 v103, v100, v100
	s_waitcnt vmcnt(6)
	v_lshlrev_b32_e32 v100, 16, v156
	v_fmac_f32_e32 v103, v100, v100
	v_and_b32_e32 v100, 0xffff0000, v156
	v_fmac_f32_e32 v103, v100, v100
	v_lshlrev_b32_e32 v100, 16, v157
	v_fmac_f32_e32 v103, v100, v100
	v_and_b32_e32 v100, 0xffff0000, v157
	v_fmac_f32_e32 v103, v100, v100
	v_lshlrev_b32_e32 v100, 16, v158
	v_fmac_f32_e32 v103, v100, v100
	v_and_b32_e32 v100, 0xffff0000, v158
	v_fmac_f32_e32 v103, v100, v100
	v_lshlrev_b32_e32 v100, 16, v159
	v_fmac_f32_e32 v103, v100, v100
	v_and_b32_e32 v100, 0xffff0000, v159
	v_fmac_f32_e32 v103, v100, v100
	v_mov_b32_e32 v100, v103
	s_nop 1
	v_permlane32_swap_b32_e32 v103, v100
	v_add_f32_e32 v103, v103, v100
	v_cmp_gt_f32_e32 vcc, s10, v103
	v_mul_f32_e32 v100, 0x4f800000, v103
	s_nop 0
	v_cndmask_b32_e32 v103, v103, v100, vcc
	v_sqrt_f32_e32 v100, v103
	s_nop 0
	v_add_u32_e32 v101, -1, v100
	v_fma_f32 v102, -v101, v100, v103
	v_cmp_ge_f32_e64 s[0:1], 0, v102
	v_add_u32_e32 v102, 1, v100
	s_nop 0
	v_cndmask_b32_e64 v101, v100, v101, s[0:1]
	v_fma_f32 v100, -v102, v100, v103
	v_cmp_lt_f32_e64 s[0:1], 0, v100
	s_nop 1
	v_cndmask_b32_e64 v100, v101, v102, s[0:1]
	v_mul_f32_e32 v101, 0x37800000, v100
	v_cndmask_b32_e32 v100, v100, v101, vcc
	v_cmp_class_f32_e32 vcc, v103, v198
	v_cndmask_b32_e32 v103, v100, v103, vcc
	v_fma_f32 v103, v214, v103, s45
	v_add_f32_e32 v64, 0x3e800000, v103
	v_add_u32_e32 v13, 0, v221
	s_mov_b32 s0, 0x100000
	s_waitcnt vmcnt(0)
	v_add_u32_e32 v30, 0, v222
	s_mov_b32 s1, 0x140000
	v_add_u32_e32 v224, 0, v223
	s_waitcnt vmcnt(5)
	ds_write_b128 v13, v[0:3]
	v_add_co_u32_e32 v0, vcc, s0, v26
	s_waitcnt vmcnt(4)
	ds_write_b128 v30, v[4:7]
	v_addc_co_u32_e32 v1, vcc, 0, v27, vcc
	v_add_co_u32_e32 v4, vcc, s1, v26
	s_waitcnt vmcnt(3)
	ds_write_b128 v224, v[8:11] offset:49152
	s_waitcnt vmcnt(2)
	ds_write_b128 v13, v[14:17] offset:16384
	s_waitcnt vmcnt(1)
	ds_write_b128 v30, v[18:21] offset:16384
	s_waitcnt vmcnt(0)
	ds_write_b128 v224, v[22:25] offset:57344
	v_addc_co_u32_e32 v5, vcc, 0, v27, vcc
	v_add_co_u32_e32 v8, vcc, s0, v28
	global_load_dwordx4 v[0:3], v[0:1], off offset:2048
	s_nop 0
	v_addc_co_u32_e32 v9, vcc, 0, v29, vcc
	global_load_dwordx4 v[4:7], v[4:5], off offset:2048
	s_nop 0
	global_load_dwordx4 v[8:11], v[8:9], off offset:1152
	s_waitcnt vmcnt(0)
	s_waitcnt vmcnt(2)
	ds_write_b128 v13, v[0:3] offset:32768
	s_waitcnt vmcnt(1)
	ds_write_b128 v30, v[4:7] offset:32768
	v_add_u32_e32 v0, 0x10000, v224
	s_waitcnt vmcnt(0)
	ds_write_b128 v0, v[8:11]
	v_lshlrev_b32_e32 v8, 7, v218
	v_and_b32_e32 v9, 0x70, v12
	v_or_b32_e32 v10, 32, v200
	v_bitop3_b32 v229, v10, v8, v9 bitop3:0xde
	v_or_b32_e32 v10, 64, v200
	v_bitop3_b32 v231, v10, v8, v9 bitop3:0xde
	v_or_b32_e32 v10, 0x60, v200
	v_bitop3_b32 v226, v200, v8, v9 bitop3:0xde
	v_bitop3_b32 v240, v10, v8, v9 bitop3:0xde
	v_add_u32_e32 v225, 0, v226
	v_add_u32_e32 v227, 0, v229
	v_add_u32_e32 v228, 0, v231
	v_add_u32_e32 v230, 0, v240
	s_waitcnt lgkmcnt(0)
	s_barrier
; #define SBAR() __builtin_amdgcn_sched_barrier(0)
; __device__ __forceinline__ void partialSM(f32x16& p0, f32x16& p1, float& m_reg, float& mn, float& alpha, int kt0, int qpos, int qw, int hi, const float* tb2, float cL, float cR) {
;   mn = m_reg; alpha = 1.f;
;   const int rel_hi = kt0 + 63 - qw, rel_lo = kt0 - (qw + 31);
;   if (rel_hi <= -91 || rel_lo >= 91) {
;     const float cm = ((rel_hi <= -91) ? cL : cR) - m_reg;
; #pragma unroll
;     for (int r = 0; r < 16; ++r) { p0[r] = fmaf(p0[r], C1, cm); p1[r] = fmaf(p1[r], C1, cm); }
;   } else {
;     const float* tp = tb2 + (kt0 - qpos + 192 + 4 * hi);
; #pragma unroll
;     for (int r4 = 0; r4 < 4; ++r4) {
;       float ta[4], tb[4];
; #pragma unroll
;       for (int i = 0; i < 4; ++i) { ta[i] = tp[8 * r4 + i] - m_reg; tb[i] = tp[32 + 8 * r4 + i] - m_reg; }
; #pragma unroll
;       for (int i = 0; i < 4; ++i) { p0[4 * r4 + i] = fmaf(p0[4 * r4 + i], C1, ta[i]); p1[4 * r4 + i] = fmaf(p1[4 * r4 + i], C1, tb[i]); }
; __device__ __forceinline__ void qkt(f32x16& p0, f32x16& p1, const char* Ks, const bf16x8* qr, int r32, int hi) {
;   bf16x8 ka[4], kb[4];
; #pragma unroll
;   for (int d0 = 0; d0 < 4; ++d0) { const int cb = (d0 * 16 + hi * 8) * 2;
;     ka[d0] = *reinterpret_cast<const bf16x8*>(Ks + KSWZ64(r32, cb)); kb[d0] = *reinterpret_cast<const bf16x8*>(Ks + KSWZ64(32 + r32, cb)); }
;   asm volatile("s_waitcnt lgkmcnt(0)" ::: "memory"); SBAR();
;   p0 = f32x16{}; p1 = f32x16{};
; #pragma unroll
;   for (int d0 = 0; d0 < 4; ++d0) {
;     p0 = __builtin_amdgcn_mfma_f32_32x32x16_bf16(ka[d0], qr[d0], p0, 0, 0, 0);
;     p1 = __builtin_amdgcn_mfma_f32_32x32x16_bf16(kb[d0], qr[d0], p1, 0, 0, 0); }
; }
	ds_read_b128 v[0:3], v225 offset:49152
	ds_read_b128 v[4:7], v225 offset:53248
	ds_read_b128 v[32:35], v227 offset:49152
	ds_read_b128 v[36:39], v227 offset:53248
	ds_read_b128 v[40:43], v228 offset:49152
	ds_read_b128 v[44:47], v228 offset:53248
	ds_read_b128 v[52:55], v230 offset:49152
	ds_read_b128 v[56:59], v230 offset:53248
	s_waitcnt lgkmcnt(0)
	s_waitcnt lgkmcnt(7)
	v_mfma_f32_32x32x16_bf16 v[16:31], v[0:3], v[164:167], 0
	s_add_i32 s4, s64, 0xffffff66
	s_mov_b64 s[0:1], -1
	s_cmp_gt_u32 s4, 0xfffffeec
	s_waitcnt lgkmcnt(6)
	v_mfma_f32_32x32x16_bf16 v[0:15], v[4:7], v[164:167], 0
	s_waitcnt lgkmcnt(5)
	v_mfma_f32_32x32x16_bf16 v[16:31], v[32:35], v[160:163], v[16:31]
	s_waitcnt lgkmcnt(4)
	v_mfma_f32_32x32x16_bf16 v[0:15], v[36:39], v[160:163], v[0:15]
	s_waitcnt lgkmcnt(3)
	v_mfma_f32_32x32x16_bf16 v[16:31], v[40:43], v[152:155], v[16:31]
	s_waitcnt lgkmcnt(2)
	v_mfma_f32_32x32x16_bf16 v[0:15], v[44:47], v[152:155], v[0:15]
	s_waitcnt lgkmcnt(1)
	v_mfma_f32_32x32x16_bf16 v[16:31], v[52:55], v[156:159], v[16:31]
	v_lshlrev_b32_e32 v52, 2, v147
	s_waitcnt lgkmcnt(0)
	v_mfma_f32_32x32x16_bf16 v[0:15], v[56:59], v[156:159], v[0:15]
	s_cbranch_scc0 .LBB0_323
	v_sub_u32_e32 v32, 0, v52
	s_mov_b32 s0, 0x12b00
	v_add3_u32 v53, v32, v200, s0
	ds_read2_b32 v[32:33], v53 offset1:1
	ds_read2_b32 v[54:55], v53 offset0:32 offset1:33
	ds_read2_b32 v[56:57], v53 offset0:34 offset1:35
	ds_read2_b32 v[34:35], v53 offset0:2 offset1:3
	ds_read2_b32 v[36:37], v53 offset0:8 offset1:9
	ds_read2_b32 v[58:59], v53 offset0:40 offset1:41
	ds_read2_b32 v[60:61], v53 offset0:42 offset1:43
	ds_read2_b32 v[38:39], v53 offset0:10 offset1:11
	ds_read2_b32 v[40:41], v53 offset0:16 offset1:17
	ds_read2_b32 v[62:63], v53 offset0:48 offset1:49
	ds_read2_b32 v[66:67], v53 offset0:50 offset1:51
	ds_read2_b32 v[42:43], v53 offset0:18 offset1:19
	ds_read2_b32 v[44:45], v53 offset0:24 offset1:25
	ds_read2_b32 v[46:47], v53 offset0:26 offset1:27
	ds_read2_b32 v[68:69], v53 offset0:58 offset1:59
	ds_read2_b32 v[70:71], v53 offset0:56 offset1:57
	s_waitcnt lgkmcnt(3)
	v_sub_f32_e32 v45, v45, v64
	v_sub_f32_e32 v44, v44, v64
	s_waitcnt lgkmcnt(2)
	v_sub_f32_e32 v47, v47, v64
	v_sub_f32_e32 v46, v46, v64
	v_sub_f32_e32 v41, v41, v64
	v_sub_f32_e32 v40, v40, v64
	v_sub_f32_e32 v43, v43, v64
	v_sub_f32_e32 v42, v42, v64
	v_sub_f32_e32 v37, v37, v64
	v_sub_f32_e32 v36, v36, v64
	v_sub_f32_e32 v39, v39, v64
	v_sub_f32_e32 v38, v38, v64
	v_sub_f32_e32 v33, v33, v64
	v_sub_f32_e32 v32, v32, v64
	v_sub_f32_e32 v35, v35, v64
	v_sub_f32_e32 v34, v34, v64
	s_waitcnt lgkmcnt(0)
	v_sub_f32_e32 v71, v71, v64
	v_sub_f32_e32 v70, v70, v64
	v_sub_f32_e32 v69, v69, v64
	v_sub_f32_e32 v68, v68, v64
	v_sub_f32_e32 v63, v63, v64
	v_sub_f32_e32 v62, v62, v64
	v_sub_f32_e32 v67, v67, v64
	v_sub_f32_e32 v66, v66, v64
	v_sub_f32_e32 v59, v59, v64
	v_sub_f32_e32 v58, v58, v64
	v_sub_f32_e32 v61, v61, v64
	v_sub_f32_e32 v60, v60, v64
	v_sub_f32_e32 v55, v55, v64
	v_sub_f32_e32 v54, v54, v64
	v_sub_f32_e32 v57, v57, v64
	v_sub_f32_e32 v56, v56, v64
	v_pk_fma_f32 v[34:35], v[18:19], s[6:7], v[34:35] op_sel_hi:[1,0,1]
	v_pk_fma_f32 v[32:33], v[16:17], s[6:7], v[32:33] op_sel_hi:[1,0,1]
	v_pk_fma_f32 v[38:39], v[22:23], s[6:7], v[38:39] op_sel_hi:[1,0,1]
	v_pk_fma_f32 v[36:37], v[20:21], s[6:7], v[36:37] op_sel_hi:[1,0,1]
	v_pk_fma_f32 v[42:43], v[26:27], s[6:7], v[42:43] op_sel_hi:[1,0,1]
	v_pk_fma_f32 v[40:41], v[24:25], s[6:7], v[40:41] op_sel_hi:[1,0,1]
	v_pk_fma_f32 v[46:47], v[30:31], s[6:7], v[46:47] op_sel_hi:[1,0,1]
	v_pk_fma_f32 v[44:45], v[28:29], s[6:7], v[44:45] op_sel_hi:[1,0,1]
	v_pk_fma_f32 v[82:83], v[2:3], s[6:7], v[56:57] op_sel_hi:[1,0,1]
	v_pk_fma_f32 v[80:81], v[0:1], s[6:7], v[54:55] op_sel_hi:[1,0,1]
	v_pk_fma_f32 v[86:87], v[6:7], s[6:7], v[60:61] op_sel_hi:[1,0,1]
	v_pk_fma_f32 v[84:85], v[4:5], s[6:7], v[58:59] op_sel_hi:[1,0,1]
	v_pk_fma_f32 v[90:91], v[10:11], s[6:7], v[66:67] op_sel_hi:[1,0,1]
	v_pk_fma_f32 v[88:89], v[8:9], s[6:7], v[62:63] op_sel_hi:[1,0,1]
	v_pk_fma_f32 v[94:95], v[14:15], s[6:7], v[68:69] op_sel_hi:[1,0,1]
	v_pk_fma_f32 v[92:93], v[12:13], s[6:7], v[70:71] op_sel_hi:[1,0,1]
	s_mov_b64 s[0:1], 0

; #define GAS __attribute__((address_space(1)))
; __device__ __forceinline__ float bf2f(unsigned short b) { return __uint_as_float(((unsigned)b) << 16); }
; __device__ __forceinline__ int v_st(int k, int c) { const int kk = (k & ~0xC) | ((k & 4) << 1) | ((k & 8) >> 1); return ((kk >> 3) * 4 + (c >> 5)) * 512 + ((kk & 7) * 32 + (c & 31)) * 2; }
; template <bool GRPB> __device__ __forceinline__ void attn_pass(const float mbK, const float bmax2, const int pass, float* __restrict__ scr, bf16* __restrict__ mixrow, const float lam, const float* __restrict__ gsub, const float one_m_li, ...
;     ...
;   const float cL = __uint_as_float(__builtin_amdgcn_readfirstlane(__float_as_uint(tb2[0]))), cR = __uint_as_float(__builtin_amdgcn_readfirstlane(__float_as_uint(tb2[384])));
;   const int qw = __builtin_amdgcn_readfirstlane(q0seq + wid * 32), qpos = qw + r32;
;   float m_reg, l_reg = 0; bf16x8 qr[4]; f32x16 o[4];
; #pragma unroll
;   for (int d = 0; d < 4; ++d) o[d] = f32x16{};
;   const bf16* Qw = Qb + (long)(wid * 32 + r32) * LDK + hi * 8;
; #pragma unroll
;   for (int d0 = 0; d0 < 4; ++d0) qr[d0] = *(const GAS bf16x8*)(Qw + d0 * 16);
;   { float qs = 0.f;
; #pragma unroll
;     for (int d0 = 0; d0 < 4; ++d0)
; #pragma unroll
;       for (int j = 0; j < 8; ++j) { const float v = bf2f((unsigned short)qr[d0][j]); qs = fmaf(v, v, qs); }
;     { auto rr = __builtin_amdgcn_permlane32_swap(__float_as_uint(qs), __float_as_uint(qs), false, false); qs = __uint_as_float(rr[0]) + __uint_as_float(rr[1]); }
;     m_reg = __builtin_sqrtf(qs) * mbK + bmax2 + 0.25f; }
;   const int sr = tid >> 4, sc = (tid & 15) * 8, vst0 = v_st(sr, sc), vst1 = v_st(32 + sr, sc);
;   const int kr = tid >> 3, kc = (tid & 7) * 8, kst = KSWZ64(kr, kc * 2);
;   const int vb0 = (int)(uintptr_t)V_lds + v_rd_base(lane);
;   struct { bf16x8 vs0, vs1, ks0; } sr_[2];
;     ...
;   f32x16 pA0, pA1, pB0, pB1; float mnA, mnB, alA, alB; bf16x8 pa0, pa1, pa2, pa3; constexpr int NT = SEQ / KVBLK;
;   __syncthreads();
;   SLOAD(0, 0); SLOAD(1, KVBLK); asm volatile("s_waitcnt vmcnt(0)" ::: "memory"); SWRITE(0, 0); SWRITE(1, 1);
; __device__ __forceinline__ void attn_phase(const Params& p, int e, char* lds) {
;     ...
;       attn_pass<false>(mbK0, bmax2, 0, scr, mix + (size_t)row0 * 1024 + h * 128, lam, p.da_subln + e * 128, one_m_li,
.LBB0_347:
	s_and_b64 vcc, exec, s[0:1]
	s_cbranch_vccz .LBB0_249
	v_readlane_b32 s0, v254, 39
	v_mov_b32_e32 v146, v232
	v_mov_b32_e32 v181, v144
	v_mov_b32_e32 v0, s0
	ds_read_b32 v0, v0
	v_readlane_b32 s0, v254, 40
	v_lshrrev_b32_e32 v2, 1, v146
	v_and_b32_e32 v180, 16, v2
	v_lshlrev_b32_e32 v8, 4, v146
	s_waitcnt lgkmcnt(0)
	v_readfirstlane_b32 s54, v0
	v_mov_b32_e32 v0, s0
	ds_read_b32 v0, v0
	s_movk_i32 s0, 0xffe0
	v_and_b32_e32 v9, 48, v8
	v_ashrrev_i32_e32 v12, 3, v146
	v_ashrrev_i32_e32 v13, 31, v12
	s_waitcnt lgkmcnt(0)
	v_readfirstlane_b32 s55, v0
	v_ashrrev_i32_e32 v0, 1, v146
	v_and_b32_e32 v1, 0xffffffe0, v0
	v_add_u32_e32 v1, s39, v1
	v_bfi_b32 v0, s0, v0, v146
	v_readfirstlane_b32 s60, v1
	v_ashrrev_i32_e32 v1, 31, v0
	v_lshlrev_b64 v[0:1], 13, v[0:1]
	v_lshl_add_u64 v[0:1], s[52:53], 0, v[0:1]
	v_lshl_add_u64 v[0:1], v[0:1], 0, v[180:181]
	global_load_dwordx4 v[164:167], v[0:1], off
	global_load_dwordx4 v[160:163], v[0:1], off offset:32
	global_load_dwordx4 v[156:159], v[0:1], off offset:64
	global_load_dwordx4 v[152:155], v[0:1], off offset:96
	s_barrier
	v_lshlrev_b64 v[52:53], 13, v[12:13]
	v_mov_b32_e32 v11, v144
	v_and_b32_e32 v147, 31, v146
	v_add_u32_e32 v190, s60, v147
	v_ashrrev_i32_e32 v2, 4, v146
	v_and_b32_e32 v3, 0xfffff0, v2
	v_lshlrev_b32_e32 v5, 1, v2
	v_lshlrev_b32_e32 v1, 3, v146
	v_and_or_b32 v3, v5, 8, v3
	v_lshrrev_b32_e32 v5, 1, v2
	v_lshrrev_b32_e32 v3, 1, v3
	v_bfe_u32 v7, v1, 5, 2
	v_and_b32_e32 v6, 3, v2
	v_or_b32_e32 v3, v3, v7
	v_and_or_b32 v5, v5, 4, v6
	v_lshlrev_b32_e32 v3, 9, v3
	v_lshlrev_b32_e32 v5, 6, v5
	v_add_u32_e32 v6, 32, v2
	v_or3_b32 v181, v3, v5, v9
	v_and_b32_e32 v3, 0xfffff0, v6
	v_lshlrev_b32_e32 v10, 1, v6
	v_and_or_b32 v3, v10, 8, v3
	v_lshrrev_b32_e32 v3, 1, v3
	v_or_b32_e32 v3, v3, v7
	v_lshlrev_b32_e32 v3, 9, v3
	v_or3_b32 v191, v3, v5, v9
	v_lshlrev_b32_e32 v3, 7, v12
	v_and_b32_e32 v10, 0x70, v8
	v_and_b32_e32 v5, 0x70, v146
	v_bitop3_b32 v192, v10, v3, v5 bitop3:0xde
	v_ashrrev_i32_e32 v3, 31, v2
	v_and_b32_e32 v4, 0x78, v1
	v_lshlrev_b64 v[50:51], 13, v[2:3]
	v_lshl_add_u64 v[2:3], s[50:51], 0, v[50:51]
	v_lshlrev_b32_e32 v8, 1, v4
	v_mov_b32_e32 v9, v144
	v_ashrrev_i32_e32 v7, 31, v6
	v_lshl_add_u64 v[18:19], v[2:3], 0, v[8:9]
	v_lshlrev_b64 v[6:7], 13, v[6:7]
	global_load_dwordx4 v[2:5], v[18:19], off offset:2048
	v_lshl_add_u64 v[6:7], s[50:51], 0, v[6:7]
	s_mov_b32 s0, 0x80000
	v_lshl_add_u64 v[6:7], v[6:7], 0, v[8:9]
	v_add_co_u32_e32 v14, vcc, s0, v18
	global_load_dwordx4 v[6:9], v[6:7], off offset:2048
	v_lshl_add_u64 v[12:13], s[50:51], 0, v[52:53]
	v_addc_co_u32_e32 v15, vcc, 0, v19, vcc
	s_mov_b32 s1, 0xc0000
	v_lshl_add_u64 v[20:21], v[12:13], 0, v[10:11]
	v_add_co_u32_e32 v22, vcc, s1, v18
	global_load_dwordx4 v[10:13], v[20:21], off offset:1024
	s_nop 0
	v_addc_co_u32_e32 v23, vcc, 0, v19, vcc
	global_load_dwordx4 v[14:17], v[14:15], off offset:2048
	v_add_co_u32_e32 v26, vcc, s0, v20
	global_load_dwordx4 v[22:25], v[22:23], off offset:2048
	s_nop 0
	v_addc_co_u32_e32 v27, vcc, 0, v21, vcc
	global_load_dwordx4 v[26:29], v[26:27], off offset:1024
	s_waitcnt vmcnt(9)
	v_lshlrev_b32_e32 v103, 16, v164
	v_fma_f32 v103, v103, v103, 0
	v_and_b32_e32 v100, 0xffff0000, v164
	v_fmac_f32_e32 v103, v100, v100
	v_lshlrev_b32_e32 v100, 16, v165
	v_fmac_f32_e32 v103, v100, v100
	v_and_b32_e32 v100, 0xffff0000, v165
	v_fmac_f32_e32 v103, v100, v100
	v_lshlrev_b32_e32 v100, 16, v166
	v_fmac_f32_e32 v103, v100, v100
	v_and_b32_e32 v100, 0xffff0000, v166
	v_fmac_f32_e32 v103, v100, v100
	v_lshlrev_b32_e32 v100, 16, v167
	v_fmac_f32_e32 v103, v100, v100
	v_and_b32_e32 v100, 0xffff0000, v167
	v_fmac_f32_e32 v103, v100, v100
	s_waitcnt vmcnt(8)
	v_lshlrev_b32_e32 v100, 16, v160
	v_fmac_f32_e32 v103, v100, v100
	v_and_b32_e32 v100, 0xffff0000, v160
	v_fmac_f32_e32 v103, v100, v100
	v_lshlrev_b32_e32 v100, 16, v161
	v_fmac_f32_e32 v103, v100, v100
	v_and_b32_e32 v100, 0xffff0000, v161
	v_fmac_f32_e32 v103, v100, v100
	v_lshlrev_b32_e32 v100, 16, v162
	v_fmac_f32_e32 v103, v100, v100
	v_and_b32_e32 v100, 0xffff0000, v162
	v_fmac_f32_e32 v103, v100, v100
	v_lshlrev_b32_e32 v100, 16, v163
	v_fmac_f32_e32 v103, v100, v100
	v_and_b32_e32 v100, 0xffff0000, v163
	v_fmac_f32_e32 v103, v100, v100
	s_waitcnt vmcnt(7)
	v_lshlrev_b32_e32 v100, 16, v156
	v_fmac_f32_e32 v103, v100, v100
	v_and_b32_e32 v100, 0xffff0000, v156
	v_fmac_f32_e32 v103, v100, v100
	v_lshlrev_b32_e32 v100, 16, v157
	v_fmac_f32_e32 v103, v100, v100
	v_and_b32_e32 v100, 0xffff0000, v157
	v_fmac_f32_e32 v103, v100, v100
	v_lshlrev_b32_e32 v100, 16, v158
	v_fmac_f32_e32 v103, v100, v100
	v_and_b32_e32 v100, 0xffff0000, v158
	v_fmac_f32_e32 v103, v100, v100
	v_lshlrev_b32_e32 v100, 16, v159
	v_fmac_f32_e32 v103, v100, v100
	v_and_b32_e32 v100, 0xffff0000, v159
	v_fmac_f32_e32 v103, v100, v100
	s_waitcnt vmcnt(6)
	v_lshlrev_b32_e32 v100, 16, v152
	v_fmac_f32_e32 v103, v100, v100
	v_and_b32_e32 v100, 0xffff0000, v152
	v_fmac_f32_e32 v103, v100, v100
	v_lshlrev_b32_e32 v100, 16, v153
	v_fmac_f32_e32 v103, v100, v100
	v_and_b32_e32 v100, 0xffff0000, v153
	v_fmac_f32_e32 v103, v100, v100
	v_lshlrev_b32_e32 v100, 16, v154
	v_fmac_f32_e32 v103, v100, v100
	v_and_b32_e32 v100, 0xffff0000, v154
	v_fmac_f32_e32 v103, v100, v100
	v_lshlrev_b32_e32 v100, 16, v155
	v_fmac_f32_e32 v103, v100, v100
	v_and_b32_e32 v100, 0xffff0000, v155
	v_fmac_f32_e32 v103, v100, v100
	v_mov_b32_e32 v100, v103
	s_nop 1
	v_permlane32_swap_b32_e32 v103, v100
	v_add_f32_e32 v103, v103, v100
	v_cmp_gt_f32_e32 vcc, s10, v103
	v_mul_f32_e32 v100, 0x4f800000, v103
	s_nop 0
	v_cndmask_b32_e32 v103, v103, v100, vcc
	v_sqrt_f32_e32 v100, v103
	s_nop 0
	v_add_u32_e32 v101, -1, v100
	v_fma_f32 v102, -v101, v100, v103
	v_cmp_ge_f32_e64 s[0:1], 0, v102
	v_add_u32_e32 v102, 1, v100
	s_nop 0
	v_cndmask_b32_e64 v101, v100, v101, s[0:1]
	v_fma_f32 v100, -v102, v100, v103
	v_cmp_lt_f32_e64 s[0:1], 0, v100
	s_nop 1
	v_cndmask_b32_e64 v100, v101, v102, s[0:1]
	v_mul_f32_e32 v101, 0x37800000, v100
	v_cndmask_b32_e32 v100, v100, v101, vcc
	v_cmp_class_f32_e32 vcc, v103, v198
	v_cndmask_b32_e32 v103, v100, v103, vcc
	v_mov_b32_e32 v0, v103
	v_add_u32_e32 v30, 0, v181
	s_mov_b32 s0, 0x100000
	s_waitcnt vmcnt(0)
; __device__ __forceinline__ int v_st(int k, int c) { const int kk = (k & ~0xC) | ((k & 4) << 1) | ((k & 8) >> 1); return ((kk >> 3) * 4 + (c >> 5)) * 512 + ((kk & 7) * 32 + (c & 31)) * 2; }
; __device__ __forceinline__ int v_rd_base(int lane) { return ((lane & 3) << 3) | (((lane >> 2) & 3) << 6) | (((lane >> 4) & 1) << 5) | (((lane >> 5) & 1) << 8); }
; __device__ __forceinline__ void partialSM(f32x16& p0, f32x16& p1, float& m_reg, float& mn, float& alpha, int kt0, int qpos, int qw, int hi, const float* tb2, float cL, float cR) {
;   mn = m_reg; alpha = 1.f;
;   const int rel_hi = kt0 + 63 - qw, rel_lo = kt0 - (qw + 31);
;   if (rel_hi <= -91 || rel_lo >= 91) {
;     const float cm = ((rel_hi <= -91) ? cL : cR) - m_reg;
; #pragma unroll
;     for (int r = 0; r < 16; ++r) { p0[r] = fmaf(p0[r], C1, cm); p1[r] = fmaf(p1[r], C1, cm); }
;   } else {
;     const float* tp = tb2 + (kt0 - qpos + 192 + 4 * hi);
; #pragma unroll
;     for (int r4 = 0; r4 < 4; ++r4) {
;       float ta[4], tb[4];
; #pragma unroll
;       for (int i = 0; i < 4; ++i) { ta[i] = tp[8 * r4 + i] - m_reg; tb[i] = tp[32 + 8 * r4 + i] - m_reg; }
; #pragma unroll
;       for (int i = 0; i < 4; ++i) { p0[4 * r4 + i] = fmaf(p0[4 * r4 + i], C1, ta[i]); p1[4 * r4 + i] = fmaf(p1[4 * r4 + i], C1, tb[i]); }
; template <bool GRPB> __device__ __forceinline__ void attn_pass(const float mbK, const float bmax2, const int pass, float* __restrict__ scr, bf16* __restrict__ mixrow, const float lam, const float* __restrict__ gsub, const float one_m_li, ...
;     ...
;     m_reg = __builtin_sqrtf(qs) * mbK + bmax2 + 0.25f; }
;   const int sr = tid >> 4, sc = (tid & 15) * 8, vst0 = v_st(sr, sc), vst1 = v_st(32 + sr, sc);
;   const int kr = tid >> 3, kc = (tid & 7) * 8, kst = KSWZ64(kr, kc * 2);
;   const int vb0 = (int)(uintptr_t)V_lds + v_rd_base(lane);
;   struct { bf16x8 vs0, vs1, ks0; } sr_[2];
;     ...
;   f32x16 pA0, pA1, pB0, pB1; float mnA, mnB, alA, alB; bf16x8 pa0, pa1, pa2, pa3; constexpr int NT = SEQ / KVBLK;
;   __syncthreads();
;   SLOAD(0, 0); SLOAD(1, KVBLK); asm volatile("s_waitcnt vmcnt(0)" ::: "memory"); SWRITE(0, 0); SWRITE(1, 1);
;   SLOAD(0, 2 * KVBLK); asm volatile("s_waitcnt vmcnt(0)" ::: "memory"); SWRITE(2, 0); __syncthreads();
;   qkt(pA0, pA1, K_lds, qr, r32, hi); partialSM(pA0, pA1, m_reg, mnA, alA, 0, qpos, qw, hi, tb2, cL, cR);
	v_add_u32_e32 v31, 0, v191
	s_mov_b32 s1, 0x140000
	v_add_u32_e32 v200, 0, v192
	v_and_b32_e32 v1, 0x70, v1
	v_fma_f32 v0, v216, v0, s45
	v_add_f32_e32 v0, 0x3e800000, v0
	s_waitcnt vmcnt(5)
	ds_write_b128 v30, v[2:5]
	v_add_co_u32_e32 v2, vcc, s0, v18
	s_waitcnt vmcnt(4)
	ds_write_b128 v31, v[6:9]
	v_addc_co_u32_e32 v3, vcc, 0, v19, vcc
	v_add_co_u32_e32 v6, vcc, s1, v18
	s_waitcnt vmcnt(3)
	ds_write_b128 v200, v[10:13] offset:49152
	s_waitcnt vmcnt(2)
	ds_write_b128 v30, v[14:17] offset:16384
	s_waitcnt vmcnt(1)
	ds_write_b128 v31, v[22:25] offset:16384
	s_waitcnt vmcnt(0)
	ds_write_b128 v200, v[26:29] offset:57344
	v_addc_co_u32_e32 v7, vcc, 0, v19, vcc
	v_add_co_u32_e32 v10, vcc, s0, v20
	global_load_dwordx4 v[2:5], v[2:3], off offset:2048
	s_nop 0
	v_addc_co_u32_e32 v11, vcc, 0, v21, vcc
	global_load_dwordx4 v[6:9], v[6:7], off offset:2048
	s_nop 0
	global_load_dwordx4 v[10:13], v[10:11], off offset:1024
	s_waitcnt vmcnt(0)
	s_waitcnt vmcnt(2)
	ds_write_b128 v30, v[2:5] offset:32768
	s_waitcnt vmcnt(1)
	ds_write_b128 v31, v[6:9] offset:32768
	v_add_u32_e32 v2, 0x10000, v200
	s_waitcnt vmcnt(0)
	ds_write_b128 v2, v[10:13]
	v_lshlrev_b32_e32 v10, 7, v147
	v_or_b32_e32 v11, 32, v180
	v_bitop3_b32 v205, v11, v10, v1 bitop3:0xde
	v_or_b32_e32 v11, 64, v180
	v_bitop3_b32 v207, v11, v10, v1 bitop3:0xde
	v_or_b32_e32 v11, 0x60, v180
	v_bitop3_b32 v202, v180, v10, v1 bitop3:0xde
	v_bitop3_b32 v208, v11, v10, v1 bitop3:0xde
	v_add_u32_e32 v201, 0, v202
	v_add_u32_e32 v203, 0, v205
	v_add_u32_e32 v204, 0, v207
	v_add_u32_e32 v206, 0, v208
	s_waitcnt lgkmcnt(0)
	s_barrier
	ds_read_b128 v[2:5], v201 offset:49152
	ds_read_b128 v[6:9], v201 offset:53248
	ds_read_b128 v[34:37], v203 offset:49152
	ds_read_b128 v[38:41], v203 offset:53248
	ds_read_b128 v[42:45], v204 offset:49152
	ds_read_b128 v[46:49], v204 offset:53248
	ds_read_b128 v[54:57], v206 offset:49152
	ds_read_b128 v[58:61], v206 offset:53248
	s_waitcnt lgkmcnt(0)
	s_waitcnt lgkmcnt(7)
	v_mfma_f32_32x32x16_bf16 v[18:33], v[2:5], v[164:167], 0
	s_add_i32 s2, s60, 0xffffff66
	s_mov_b64 s[0:1], -1
	s_cmp_gt_u32 s2, 0xfffffeec
	s_waitcnt lgkmcnt(6)
	v_mfma_f32_32x32x16_bf16 v[2:17], v[6:9], v[164:167], 0
	s_waitcnt lgkmcnt(5)
	v_mfma_f32_32x32x16_bf16 v[18:33], v[34:37], v[160:163], v[18:33]
	s_waitcnt lgkmcnt(4)
	v_mfma_f32_32x32x16_bf16 v[2:17], v[38:41], v[160:163], v[2:17]
	s_waitcnt lgkmcnt(3)
	v_mfma_f32_32x32x16_bf16 v[18:33], v[42:45], v[156:159], v[18:33]
	s_waitcnt lgkmcnt(2)
	v_mfma_f32_32x32x16_bf16 v[2:17], v[46:49], v[156:159], v[2:17]
	s_waitcnt lgkmcnt(1)
	v_mfma_f32_32x32x16_bf16 v[18:33], v[54:57], v[152:155], v[18:33]
	v_lshlrev_b32_e32 v54, 2, v190
	s_waitcnt lgkmcnt(0)
	v_mfma_f32_32x32x16_bf16 v[2:17], v[58:61], v[152:155], v[2:17]
	s_cbranch_scc0 .LBB0_350
	v_sub_u32_e32 v1, 0, v54
	s_mov_b32 s0, 0x12b00
	v_add3_u32 v1, v1, v180, s0
	ds_read2_b32 v[34:35], v1 offset1:1
	ds_read2_b32 v[56:57], v1 offset0:32 offset1:33
	ds_read2_b32 v[58:59], v1 offset0:34 offset1:35
	ds_read2_b32 v[36:37], v1 offset0:2 offset1:3
	ds_read2_b32 v[38:39], v1 offset0:8 offset1:9
	ds_read2_b32 v[60:61], v1 offset0:40 offset1:41
	ds_read2_b32 v[62:63], v1 offset0:42 offset1:43
	ds_read2_b32 v[40:41], v1 offset0:10 offset1:11
	ds_read2_b32 v[42:43], v1 offset0:16 offset1:17
	ds_read2_b32 v[64:65], v1 offset0:48 offset1:49
	ds_read2_b32 v[66:67], v1 offset0:50 offset1:51
	ds_read2_b32 v[44:45], v1 offset0:18 offset1:19
	ds_read2_b32 v[46:47], v1 offset0:24 offset1:25
	ds_read2_b32 v[48:49], v1 offset0:26 offset1:27
	ds_read2_b32 v[68:69], v1 offset0:58 offset1:59
	ds_read2_b32 v[70:71], v1 offset0:56 offset1:57
	s_waitcnt lgkmcnt(3)
	v_sub_f32_e32 v47, v47, v0
	v_sub_f32_e32 v46, v46, v0
	s_waitcnt lgkmcnt(2)
	v_sub_f32_e32 v49, v49, v0
	v_sub_f32_e32 v48, v48, v0
	v_sub_f32_e32 v43, v43, v0
	v_sub_f32_e32 v42, v42, v0
	v_sub_f32_e32 v45, v45, v0
	v_sub_f32_e32 v44, v44, v0
	v_sub_f32_e32 v39, v39, v0
	v_sub_f32_e32 v38, v38, v0
	v_sub_f32_e32 v41, v41, v0
	v_sub_f32_e32 v40, v40, v0
	v_sub_f32_e32 v35, v35, v0
	v_sub_f32_e32 v34, v34, v0
	v_sub_f32_e32 v37, v37, v0
	v_sub_f32_e32 v36, v36, v0
	s_waitcnt lgkmcnt(0)
	v_sub_f32_e32 v71, v71, v0
	v_sub_f32_e32 v70, v70, v0
	v_sub_f32_e32 v69, v69, v0
	v_sub_f32_e32 v68, v68, v0
	v_sub_f32_e32 v65, v65, v0
	v_sub_f32_e32 v64, v64, v0
	v_sub_f32_e32 v67, v67, v0
	v_sub_f32_e32 v66, v66, v0
	v_sub_f32_e32 v61, v61, v0
	v_sub_f32_e32 v60, v60, v0
	v_sub_f32_e32 v63, v63, v0
	v_sub_f32_e32 v62, v62, v0
	v_sub_f32_e32 v57, v57, v0
	v_sub_f32_e32 v56, v56, v0
	v_sub_f32_e32 v59, v59, v0
	v_sub_f32_e32 v58, v58, v0
	v_pk_fma_f32 v[36:37], v[20:21], s[6:7], v[36:37] op_sel_hi:[1,0,1]
	v_pk_fma_f32 v[34:35], v[18:19], s[6:7], v[34:35] op_sel_hi:[1,0,1]
	v_pk_fma_f32 v[40:41], v[24:25], s[6:7], v[40:41] op_sel_hi:[1,0,1]
	v_pk_fma_f32 v[38:39], v[22:23], s[6:7], v[38:39] op_sel_hi:[1,0,1]
	v_pk_fma_f32 v[44:45], v[28:29], s[6:7], v[44:45] op_sel_hi:[1,0,1]
	v_pk_fma_f32 v[42:43], v[26:27], s[6:7], v[42:43] op_sel_hi:[1,0,1]
	v_pk_fma_f32 v[48:49], v[32:33], s[6:7], v[48:49] op_sel_hi:[1,0,1]
	v_pk_fma_f32 v[46:47], v[30:31], s[6:7], v[46:47] op_sel_hi:[1,0,1]
	v_pk_fma_f32 v[82:83], v[4:5], s[6:7], v[58:59] op_sel_hi:[1,0,1]
	v_pk_fma_f32 v[80:81], v[2:3], s[6:7], v[56:57] op_sel_hi:[1,0,1]
	v_pk_fma_f32 v[86:87], v[8:9], s[6:7], v[62:63] op_sel_hi:[1,0,1]
	v_pk_fma_f32 v[84:85], v[6:7], s[6:7], v[60:61] op_sel_hi:[1,0,1]
	v_pk_fma_f32 v[90:91], v[12:13], s[6:7], v[66:67] op_sel_hi:[1,0,1]
	v_pk_fma_f32 v[88:89], v[10:11], s[6:7], v[64:65] op_sel_hi:[1,0,1]
	v_pk_fma_f32 v[94:95], v[16:17], s[6:7], v[68:69] op_sel_hi:[1,0,1]
	v_pk_fma_f32 v[92:93], v[14:15], s[6:7], v[70:71] op_sel_hi:[1,0,1]
	s_mov_b64 s[0:1], 0
